# att16 = att15 + same conv-stage load de-serialisation in the tile-summary pass (rnn0 in P2)
# speedup vs baseline: 1.0001x; 1.0001x over previous
.LBB0_389:
	s_or_b64 exec, exec, s[24:25]
	v_ashrrev_i32_e32 v55, 31, v54
	v_lshl_add_u64 v[58:59], s[42:43], 0, v[54:55]
	v_lshlrev_b64 v[58:59], 11, v[58:59]
	v_lshl_add_u64 v[58:59], v[52:53], 0, v[58:59]
	global_load_dwordx4 v[84:87], v[58:59], off
	s_mov_b64 s[98:99], 0x1000
	global_load_dwordx4 v[88:91], v[58:59], off offset:2048
	v_lshl_add_u64 v[216:217], v[58:59], 0, s[98:99]
	global_load_dwordx4 v[160:163], v[216:217], off
	global_load_dwordx4 v[164:167], v[216:217], off offset:2048
	v_lshl_add_u64 v[216:217], v[216:217], 0, s[98:99]
	global_load_dwordx4 v[168:171], v[216:217], off
	global_load_dwordx4 v[172:175], v[216:217], off offset:2048
	v_lshl_add_u64 v[216:217], v[216:217], 0, s[98:99]
	global_load_dwordx4 v[176:179], v[216:217], off
	global_load_dwordx4 v[180:183], v[216:217], off offset:2048
	v_lshl_add_u64 v[216:217], v[216:217], 0, s[98:99]
	global_load_dwordx4 v[184:187], v[216:217], off
	global_load_dwordx4 v[188:191], v[216:217], off offset:2048
	v_lshl_add_u64 v[216:217], v[216:217], 0, s[98:99]
	global_load_dwordx4 v[192:195], v[216:217], off
	global_load_dwordx4 v[196:199], v[216:217], off offset:2048
	v_lshl_add_u64 v[216:217], v[216:217], 0, s[98:99]
	global_load_dwordx4 v[200:203], v[216:217], off
	global_load_dwordx4 v[204:207], v[216:217], off offset:2048
	v_lshl_add_u64 v[216:217], v[216:217], 0, s[98:99]
	global_load_dwordx4 v[208:211], v[216:217], off
	global_load_dwordx4 v[212:215], v[216:217], off offset:2048
	s_waitcnt vmcnt(16)
	v_lshlrev_b32_e32 v66, 16, v46
	v_and_b32_e32 v76, 0xffff0000, v46
	v_mov_b32_e32 v46, v32
	v_mov_b32_e32 v32, v0
	v_or_b32_e32 v0, 1, v54
	v_lshlrev_b32_e32 v67, 16, v47
	v_and_b32_e32 v77, 0xffff0000, v47
	v_mov_b32_e32 v47, v34
	v_mov_b32_e32 v34, v33
	v_mov_b32_e32 v33, v2
	v_mov_b32_e32 v2, v1
	v_ashrrev_i32_e32 v1, 31, v0
	v_lshl_add_u64 v[0:1], s[42:43], 0, v[0:1]
	v_lshlrev_b64 v[0:1], 11, v[0:1]
	v_lshl_add_u64 v[0:1], v[52:53], 0, v[0:1]
	v_lshlrev_b32_e32 v60, 16, v40
	v_and_b32_e32 v58, 0xffff0000, v40
	v_mov_b32_e32 v40, v24
	v_mov_b32_e32 v24, v8
	v_or_b32_e32 v8, 2, v54
	v_lshlrev_b32_e32 v61, 16, v41
	v_and_b32_e32 v59, 0xffff0000, v41
	v_mov_b32_e32 v41, v26
	v_mov_b32_e32 v26, v25
	v_mov_b32_e32 v25, v10
	v_mov_b32_e32 v10, v9
	v_ashrrev_i32_e32 v9, 31, v8
	v_lshlrev_b32_e32 v71, 16, v51
	v_lshlrev_b32_e32 v70, 16, v50
	v_and_b32_e32 v69, 0xffff0000, v51
	v_and_b32_e32 v68, 0xffff0000, v50
	v_lshlrev_b32_e32 v62, 16, v44
	v_lshlrev_b32_e32 v63, 16, v45
	v_mov_b32_e32 v50, v36
	v_mov_b32_e32 v51, v38
	v_lshl_add_u64 v[8:9], s[42:43], 0, v[8:9]
	v_lshlrev_b32_e32 v75, 16, v49
	v_lshlrev_b32_e32 v74, 16, v48
	v_and_b32_e32 v73, 0xffff0000, v49
	v_and_b32_e32 v72, 0xffff0000, v48
	v_mov_b32_e32 v48, v20
	v_mov_b32_e32 v49, v22
	v_mov_b32_e32 v22, v21
	v_mov_b32_e32 v20, v12
	v_mov_b32_e32 v21, v14
	v_mov_b32_e32 v14, v13
	v_mov_b32_e32 v12, v16
	v_mov_b32_e32 v13, v18
	v_mov_b32_e32 v18, v17
	v_pk_fma_f32 v[16:17], v[46:47], v[62:63], v[50:51]
	v_lshlrev_b64 v[8:9], 11, v[8:9]
	v_and_b32_e32 v64, 0xffff0000, v44
	v_and_b32_e32 v65, 0xffff0000, v45
	v_mov_b32_e32 v38, v37
	v_pk_fma_f32 v[16:17], v[48:49], v[74:75], v[16:17]
	v_lshl_add_u64 v[8:9], v[52:53], 0, v[8:9]
	v_lshl_add_u32 v44, v56, 1, 0
	v_mov_b32_e32 v56, v28
	v_mov_b32_e32 v57, v30
	v_mov_b32_e32 v30, v29
	v_lshlrev_b32_e32 v81, 16, v43
	v_lshlrev_b32_e32 v80, 16, v42
	v_and_b32_e32 v79, 0xffff0000, v43
	v_and_b32_e32 v78, 0xffff0000, v42
	v_pk_fma_f32 v[28:29], v[34:35], v[64:65], v[38:39]
	v_pk_fma_f32 v[36:37], v[20:21], v[66:67], v[12:13]
	v_pk_fma_f32 v[42:43], v[14:15], v[76:77], v[18:19]
	v_pk_fma_f32 v[76:77], v[40:41], v[60:61], v[16:17]
	v_pk_fma_f32 v[28:29], v[22:23], v[72:73], v[28:29]
	v_pk_fma_f32 v[42:43], v[2:3], v[68:69], v[42:43]
	v_pk_fma_f32 v[28:29], v[26:27], v[58:59], v[28:29]
	v_pk_fma_f32 v[36:37], v[32:33], v[70:71], v[36:37]
	v_pk_fma_f32 v[68:69], v[14:15], v[68:69], v[18:19]
	v_pk_fma_f32 v[70:71], v[20:21], v[70:71], v[12:13]
	v_pk_fma_f32 v[68:69], v[2:3], v[78:79], v[68:69]
	v_pk_fma_f32 v[70:71], v[32:33], v[80:81], v[70:71]
	s_ashr_i32 s19, s19, 1
	v_bfe_u32 v96, v82, 5, 1
	s_waitcnt vmcnt(15)
	v_lshlrev_b32_e32 v67, 16, v85
	v_lshlrev_b32_e32 v66, 16, v84
	v_and_b32_e32 v65, 0xffff0000, v85
	v_and_b32_e32 v64, 0xffff0000, v84
	v_lshlrev_b32_e32 v63, 16, v87
	v_lshlrev_b32_e32 v62, 16, v86
	v_and_b32_e32 v17, 0xffff0000, v87
	v_and_b32_e32 v16, 0xffff0000, v86
	v_pk_fma_f32 v[28:29], v[30:31], v[64:65], v[28:29]
	v_mov_b32_e32 v1, v6
	v_pk_fma_f32 v[76:77], v[56:57], v[66:67], v[76:77]
	v_mov_b32_e32 v6, v5
	v_bfe_u32 v45, v29, 16, 1
	v_bfe_u32 v8, v28, 16, 1
	v_mov_b32_e32 v0, v4
	v_pk_fma_f32 v[4:5], v[6:7], v[78:79], v[42:43]
	v_add3_u32 v8, v28, v8, s27
	v_add3_u32 v9, v29, v45, s27
	v_bfe_u32 v28, v76, 16, 1
	v_bfe_u32 v29, v77, 16, 1
	v_pk_fma_f32 v[36:37], v[0:1], v[80:81], v[36:37]
	v_pk_fma_f32 v[4:5], v[10:11], v[16:17], v[4:5]
	v_add3_u32 v29, v77, v29, s27
	v_add3_u32 v28, v76, v28, s27
	v_pk_fma_f32 v[36:37], v[24:25], v[62:63], v[36:37]
	v_bfe_u32 v42, v5, 16, 1
	v_bfe_u32 v43, v4, 16, 1
	v_lshrrev_b32_e32 v28, 16, v28
	v_lshrrev_b32_e32 v29, 16, v29
	v_add3_u32 v4, v4, v43, s27
	v_add3_u32 v5, v5, v42, s27
	v_bfe_u32 v42, v36, 16, 1
	v_bfe_u32 v43, v37, 16, 1
	v_and_or_b32 v93, v9, s26, v29
	v_and_or_b32 v92, v8, s26, v28
	v_pk_fma_f32 v[28:29], v[46:47], v[74:75], v[50:51]
	v_add3_u32 v37, v37, v43, s27
	v_add3_u32 v36, v36, v42, s27
	v_pk_fma_f32 v[28:29], v[48:49], v[60:61], v[28:29]
	v_lshrrev_b32_e32 v36, 16, v36
	v_lshrrev_b32_e32 v37, 16, v37
	s_waitcnt vmcnt(14)
	v_lshlrev_b32_e32 v77, 16, v89
	v_lshlrev_b32_e32 v76, 16, v88
	v_pk_fma_f32 v[28:29], v[40:41], v[66:67], v[28:29]
	v_and_or_b32 v95, v5, s26, v37
	v_and_or_b32 v94, v4, s26, v36
	v_pk_fma_f32 v[36:37], v[56:57], v[76:77], v[28:29]
	v_pk_fma_f32 v[28:29], v[34:35], v[72:73], v[38:39]
	v_or_b32_e32 v72, 3, v54
	v_pk_fma_f32 v[28:29], v[22:23], v[58:59], v[28:29]
	v_ashrrev_i32_e32 v73, 31, v72
	v_and_b32_e32 v9, 0xffff0000, v89
	v_and_b32_e32 v8, 0xffff0000, v88
	v_pk_fma_f32 v[28:29], v[26:27], v[64:65], v[28:29]
	v_lshl_add_u64 v[72:73], s[42:43], 0, v[72:73]
	v_pk_fma_f32 v[42:43], v[30:31], v[8:9], v[28:29]
	v_and_b32_e32 v29, 0xffff0000, v91
	v_and_b32_e32 v28, 0xffff0000, v90
	v_pk_fma_f32 v[68:69], v[6:7], v[16:17], v[68:69]
	v_lshlrev_b64 v[72:73], 11, v[72:73]
	v_lshlrev_b32_e32 v75, 16, v91
	v_lshlrev_b32_e32 v74, 16, v90
	v_pk_fma_f32 v[70:71], v[0:1], v[62:63], v[70:71]
	v_pk_fma_f32 v[68:69], v[10:11], v[28:29], v[68:69]
	v_lshl_add_u64 v[72:73], v[52:53], 0, v[72:73]
	v_mad_u64_u32 v[4:5], s[0:1], v54, s30, v[44:45]
	v_pk_fma_f32 v[70:71], v[24:25], v[74:75], v[70:71]
	v_bfe_u32 v45, v68, 16, 1
	v_bfe_u32 v55, v43, 16, 1
	v_bfe_u32 v72, v42, 16, 1
	v_bfe_u32 v5, v69, 16, 1
	v_add3_u32 v42, v42, v72, s27
	v_add3_u32 v43, v43, v55, s27
	v_add3_u32 v45, v68, v45, s27
	v_bfe_u32 v55, v36, 16, 1
	v_bfe_u32 v68, v37, 16, 1
	v_bfe_u32 v72, v71, 16, 1
	v_add3_u32 v5, v69, v5, s27
	v_bfe_u32 v69, v70, 16, 1
	v_add3_u32 v71, v71, v72, s27
	v_add3_u32 v37, v37, v68, s27
	v_add3_u32 v36, v36, v55, s27
	v_add3_u32 v69, v70, v69, s27
	v_lshrrev_b32_e32 v36, 16, v36
	v_lshrrev_b32_e32 v37, 16, v37
	v_lshrrev_b32_e32 v68, 16, v71
	v_lshrrev_b32_e32 v55, 16, v69
	v_and_or_b32 v71, v5, s26, v68
	v_and_or_b32 v69, v43, s26, v37
	v_and_or_b32 v68, v42, s26, v36
	v_pk_fma_f32 v[42:43], v[46:47], v[60:61], v[50:51]
	s_waitcnt vmcnt(13)
	v_lshlrev_b32_e32 v73, 16, v161
	v_pk_fma_f32 v[42:43], v[48:49], v[66:67], v[42:43]
	v_lshlrev_b32_e32 v72, 16, v160
	v_pk_fma_f32 v[42:43], v[40:41], v[76:77], v[42:43]
	v_pk_fma_f32 v[78:79], v[14:15], v[78:79], v[18:19]
	v_pk_fma_f32 v[60:61], v[56:57], v[72:73], v[42:43]
	v_pk_fma_f32 v[42:43], v[34:35], v[58:59], v[38:39]
	v_and_b32_e32 v37, 0xffff0000, v161
	v_pk_fma_f32 v[42:43], v[22:23], v[64:65], v[42:43]
	v_and_b32_e32 v36, 0xffff0000, v160
	v_pk_fma_f32 v[42:43], v[26:27], v[8:9], v[42:43]
	v_pk_fma_f32 v[78:79], v[2:3], v[16:17], v[78:79]
	v_pk_fma_f32 v[58:59], v[30:31], v[36:37], v[42:43]
	v_and_b32_e32 v43, 0xffff0000, v163
	v_and_b32_e32 v42, 0xffff0000, v162
	v_pk_fma_f32 v[78:79], v[6:7], v[28:29], v[78:79]
	v_and_or_b32 v70, v45, s26, v55
	v_pk_fma_f32 v[84:85], v[10:11], v[42:43], v[78:79]
	v_or_b32_e32 v78, 4, v54
	v_ashrrev_i32_e32 v79, 31, v78
	v_lshl_add_u64 v[78:79], s[42:43], 0, v[78:79]
	v_lshlrev_b64 v[78:79], 11, v[78:79]
	ds_write_b128 v4, v[68:71] offset:528
	v_pk_fma_f32 v[68:69], v[20:21], v[80:81], v[12:13]
	v_lshl_add_u64 v[78:79], v[52:53], 0, v[78:79]
	v_bfe_u32 v55, v59, 16, 1
	v_pk_fma_f32 v[68:69], v[32:33], v[62:63], v[68:69]
	v_bfe_u32 v45, v84, 16, 1
	v_add3_u32 v55, v59, v55, s27
	v_bfe_u32 v59, v60, 16, 1
	v_lshlrev_b32_e32 v71, 16, v163
	v_lshlrev_b32_e32 v70, 16, v162
	v_pk_fma_f32 v[68:69], v[0:1], v[74:75], v[68:69]
	v_bfe_u32 v86, v58, 16, 1
	v_add3_u32 v45, v84, v45, s27
	v_bfe_u32 v84, v61, 16, 1
	v_add3_u32 v59, v60, v59, s27
	v_pk_fma_f32 v[68:69], v[24:25], v[70:71], v[68:69]
	v_bfe_u32 v5, v85, 16, 1
	v_add3_u32 v58, v58, v86, s27
	v_add3_u32 v61, v61, v84, s27
	v_lshrrev_b32_e32 v84, 16, v59
	v_add3_u32 v5, v85, v5, s27
	v_bfe_u32 v85, v68, 16, 1
	v_and_or_b32 v58, v58, s26, v84
	v_or_b32_e32 v84, 5, v54
	v_add3_u32 v68, v68, v85, s27
	v_ashrrev_i32_e32 v85, 31, v84
	v_lshl_add_u64 v[84:85], s[42:43], 0, v[84:85]
	v_lshlrev_b64 v[84:85], 11, v[84:85]
	v_bfe_u32 v86, v69, 16, 1
	v_lshl_add_u64 v[84:85], v[52:53], 0, v[84:85]
	v_add3_u32 v69, v69, v86, s27
	v_lshrrev_b32_e32 v59, 16, v61
	v_lshrrev_b32_e32 v60, 16, v68
	v_lshrrev_b32_e32 v61, 16, v69
	v_and_or_b32 v61, v5, s26, v61
	v_and_or_b32 v60, v45, s26, v60
	v_and_or_b32 v59, v55, s26, v59
	ds_write_b128 v4, v[58:61] offset:1056
	v_pk_fma_f32 v[60:61], v[46:47], v[66:67], v[50:51]
	s_waitcnt vmcnt(12)
	v_lshlrev_b32_e32 v69, 16, v165
	v_pk_fma_f32 v[60:61], v[48:49], v[76:77], v[60:61]
	v_lshlrev_b32_e32 v68, 16, v164
	v_pk_fma_f32 v[60:61], v[40:41], v[72:73], v[60:61]
	v_and_b32_e32 v59, 0xffff0000, v165
	v_and_b32_e32 v58, 0xffff0000, v164
	v_pk_fma_f32 v[88:89], v[56:57], v[68:69], v[60:61]
	v_pk_fma_f32 v[60:61], v[34:35], v[64:65], v[38:39]
	v_pk_fma_f32 v[16:17], v[14:15], v[16:17], v[18:19]
	v_pk_fma_f32 v[60:61], v[22:23], v[8:9], v[60:61]
	v_pk_fma_f32 v[62:63], v[20:21], v[62:63], v[12:13]
	v_pk_fma_f32 v[60:61], v[26:27], v[36:37], v[60:61]
	v_pk_fma_f32 v[16:17], v[2:3], v[28:29], v[16:17]
	v_pk_fma_f32 v[64:65], v[30:31], v[58:59], v[60:61]
	v_and_b32_e32 v61, 0xffff0000, v167
	v_and_b32_e32 v60, 0xffff0000, v166
	v_pk_fma_f32 v[62:63], v[32:33], v[74:75], v[62:63]
	v_pk_fma_f32 v[16:17], v[6:7], v[42:43], v[16:17]
	v_lshlrev_b32_e32 v67, 16, v167
	v_lshlrev_b32_e32 v66, 16, v166
	v_pk_fma_f32 v[62:63], v[0:1], v[70:71], v[62:63]
	v_pk_fma_f32 v[16:17], v[10:11], v[60:61], v[16:17]
	v_pk_fma_f32 v[62:63], v[24:25], v[66:67], v[62:63]
	v_bfe_u32 v5, v17, 16, 1
	v_bfe_u32 v45, v16, 16, 1
	v_bfe_u32 v55, v65, 16, 1
	v_bfe_u32 v90, v64, 16, 1
	v_add3_u32 v90, v64, v90, s27
	v_add3_u32 v55, v65, v55, s27
	v_add3_u32 v16, v16, v45, s27
	v_add3_u32 v5, v17, v5, s27
	v_bfe_u32 v17, v88, 16, 1
	v_bfe_u32 v45, v89, 16, 1
	v_bfe_u32 v64, v62, 16, 1
	v_bfe_u32 v65, v63, 16, 1
	v_add3_u32 v63, v63, v65, s27
	v_add3_u32 v62, v62, v64, s27
	v_add3_u32 v45, v89, v45, s27
	v_add3_u32 v17, v88, v17, s27
	v_lshrrev_b32_e32 v17, 16, v17
	v_lshrrev_b32_e32 v45, 16, v45
	v_lshrrev_b32_e32 v62, 16, v62
	v_lshrrev_b32_e32 v63, 16, v63
	v_and_or_b32 v65, v5, s26, v63
	v_and_or_b32 v64, v16, s26, v62
	v_and_or_b32 v63, v55, s26, v45
	v_and_or_b32 v62, v90, s26, v17
	ds_write_b128 v4, v[62:65] offset:1584
	v_pk_fma_f32 v[62:63], v[46:47], v[76:77], v[50:51]
	v_or_b32_e32 v76, 6, v54
	v_ashrrev_i32_e32 v77, 31, v76
	v_lshl_add_u64 v[76:77], s[42:43], 0, v[76:77]
	v_lshlrev_b64 v[76:77], 11, v[76:77]
	v_lshl_add_u64 v[76:77], v[52:53], 0, v[76:77]
	s_waitcnt vmcnt(11)
	v_lshlrev_b32_e32 v65, 16, v169
	v_lshlrev_b32_e32 v64, 16, v168
	v_and_b32_e32 v17, 0xffff0000, v169
	v_and_b32_e32 v16, 0xffff0000, v168
	v_pk_fma_f32 v[8:9], v[34:35], v[8:9], v[38:39]
	v_pk_fma_f32 v[62:63], v[48:49], v[72:73], v[62:63]
	v_pk_fma_f32 v[8:9], v[22:23], v[36:37], v[8:9]
	v_pk_fma_f32 v[74:75], v[20:21], v[74:75], v[12:13]
	v_pk_fma_f32 v[28:29], v[14:15], v[28:29], v[18:19]
	v_pk_fma_f32 v[62:63], v[40:41], v[68:69], v[62:63]
	v_pk_fma_f32 v[8:9], v[26:27], v[58:59], v[8:9]
	v_pk_fma_f32 v[74:75], v[32:33], v[70:71], v[74:75]
	v_pk_fma_f32 v[28:29], v[2:3], v[42:43], v[28:29]
	v_pk_fma_f32 v[88:89], v[56:57], v[64:65], v[62:63]
	v_pk_fma_f32 v[90:91], v[30:31], v[16:17], v[8:9]
	v_lshlrev_b32_e32 v63, 16, v171
	v_lshlrev_b32_e32 v62, 16, v170
	v_and_b32_e32 v9, 0xffff0000, v171
	v_and_b32_e32 v8, 0xffff0000, v170
	v_pk_fma_f32 v[74:75], v[0:1], v[66:67], v[74:75]
	v_pk_fma_f32 v[28:29], v[6:7], v[60:61], v[28:29]
	v_pk_fma_f32 v[74:75], v[24:25], v[62:63], v[74:75]
	v_pk_fma_f32 v[28:29], v[10:11], v[8:9], v[28:29]
	v_bfe_u32 v80, v90, 16, 1
	v_bfe_u32 v5, v29, 16, 1
	v_bfe_u32 v81, v74, 16, 1
	v_bfe_u32 v45, v28, 16, 1
	v_add3_u32 v80, v90, v80, s27
	v_add3_u32 v5, v29, v5, s27
	v_bfe_u32 v29, v88, 16, 1
	v_bfe_u32 v90, v75, 16, 1
	v_add3_u32 v74, v74, v81, s27
	v_add3_u32 v28, v28, v45, s27
	v_add3_u32 v75, v75, v90, s27
	v_add3_u32 v29, v88, v29, s27
	v_lshrrev_b32_e32 v74, 16, v74
	v_bfe_u32 v55, v91, 16, 1
	v_lshrrev_b32_e32 v29, 16, v29
	v_lshrrev_b32_e32 v75, 16, v75
	v_and_or_b32 v90, v28, s26, v74
	s_waitcnt vmcnt(10)
	v_lshlrev_b32_e32 v74, 16, v172
	v_and_b32_e32 v28, 0xffff0000, v172
	v_or_b32_e32 v84, 7, v54
	v_add3_u32 v55, v91, v55, s27
	v_bfe_u32 v45, v89, 16, 1
	v_and_or_b32 v91, v5, s26, v75
	v_and_or_b32 v88, v80, s26, v29
	v_lshlrev_b32_e32 v75, 16, v173
	v_and_b32_e32 v29, 0xffff0000, v173
	v_ashrrev_i32_e32 v85, 31, v84
	v_add3_u32 v45, v89, v45, s27
	v_pk_fma_f32 v[72:73], v[46:47], v[72:73], v[50:51]
	v_pk_fma_f32 v[36:37], v[34:35], v[36:37], v[38:39]
	v_lshl_add_u64 v[84:85], s[42:43], 0, v[84:85]
	v_lshrrev_b32_e32 v45, 16, v45
	v_pk_fma_f32 v[72:73], v[48:49], v[68:69], v[72:73]
	v_pk_fma_f32 v[36:37], v[22:23], v[58:59], v[36:37]
	v_lshlrev_b64 v[84:85], 11, v[84:85]
	v_and_or_b32 v89, v55, s26, v45
	v_pk_fma_f32 v[72:73], v[40:41], v[64:65], v[72:73]
	v_pk_fma_f32 v[36:37], v[26:27], v[16:17], v[36:37]
	v_lshl_add_u64 v[84:85], v[52:53], 0, v[84:85]
	ds_write_b128 v4, v[88:91] offset:2112
	v_pk_fma_f32 v[80:81], v[56:57], v[74:75], v[72:73]
	v_pk_fma_f32 v[88:89], v[30:31], v[28:29], v[36:37]
	v_lshlrev_b32_e32 v73, 16, v175
	v_lshlrev_b32_e32 v72, 16, v174
	v_and_b32_e32 v37, 0xffff0000, v175
	v_and_b32_e32 v36, 0xffff0000, v174
	v_pk_fma_f32 v[42:43], v[14:15], v[42:43], v[18:19]
	v_pk_fma_f32 v[70:71], v[20:21], v[70:71], v[12:13]
	v_pk_fma_f32 v[42:43], v[2:3], v[60:61], v[42:43]
	v_pk_fma_f32 v[70:71], v[32:33], v[66:67], v[70:71]
	v_pk_fma_f32 v[42:43], v[6:7], v[8:9], v[42:43]
	v_pk_fma_f32 v[70:71], v[0:1], v[62:63], v[70:71]
	v_pk_fma_f32 v[42:43], v[10:11], v[36:37], v[42:43]
	v_pk_fma_f32 v[70:71], v[24:25], v[72:73], v[70:71]
	v_bfe_u32 v5, v43, 16, 1
	v_bfe_u32 v45, v42, 16, 1
	v_bfe_u32 v55, v89, 16, 1
	v_bfe_u32 v90, v88, 16, 1
	v_add3_u32 v88, v88, v90, s27
	v_add3_u32 v55, v89, v55, s27
	v_add3_u32 v42, v42, v45, s27
	v_add3_u32 v5, v43, v5, s27
	v_bfe_u32 v43, v80, 16, 1
	v_bfe_u32 v45, v81, 16, 1
	v_bfe_u32 v89, v70, 16, 1
	v_bfe_u32 v90, v71, 16, 1
	v_add3_u32 v71, v71, v90, s27
	v_add3_u32 v70, v70, v89, s27
	v_add3_u32 v45, v81, v45, s27
	v_add3_u32 v43, v80, v43, s27
	v_pk_fma_f32 v[68:69], v[46:47], v[68:69], v[50:51]
	v_pk_fma_f32 v[58:59], v[34:35], v[58:59], v[38:39]
	v_lshrrev_b32_e32 v43, 16, v43
	v_lshrrev_b32_e32 v45, 16, v45
	v_lshrrev_b32_e32 v70, 16, v70
	v_lshrrev_b32_e32 v71, 16, v71
	v_pk_fma_f32 v[68:69], v[48:49], v[64:65], v[68:69]
	v_pk_fma_f32 v[58:59], v[22:23], v[16:17], v[58:59]
	v_and_or_b32 v91, v5, s26, v71
	v_and_or_b32 v90, v42, s26, v70
	v_and_or_b32 v89, v55, s26, v45
	v_and_or_b32 v88, v88, s26, v43
	s_waitcnt vmcnt(9)
	v_lshlrev_b32_e32 v71, 16, v177
	v_lshlrev_b32_e32 v70, 16, v176
	v_and_b32_e32 v43, 0xffff0000, v177
	v_and_b32_e32 v42, 0xffff0000, v176
	v_pk_fma_f32 v[68:69], v[40:41], v[74:75], v[68:69]
	v_pk_fma_f32 v[58:59], v[26:27], v[28:29], v[58:59]
	ds_write_b128 v4, v[88:91] offset:2640
	v_pk_fma_f32 v[76:77], v[56:57], v[70:71], v[68:69]
	v_pk_fma_f32 v[88:89], v[30:31], v[42:43], v[58:59]
	v_lshlrev_b32_e32 v68, 16, v178
	v_and_b32_e32 v58, 0xffff0000, v178
	v_or_b32_e32 v78, 8, v54
	v_lshlrev_b32_e32 v69, 16, v179
	v_and_b32_e32 v59, 0xffff0000, v179
	v_ashrrev_i32_e32 v79, 31, v78
	v_lshl_add_u64 v[78:79], s[42:43], 0, v[78:79]
	v_lshlrev_b64 v[78:79], 11, v[78:79]
	v_pk_fma_f32 v[60:61], v[14:15], v[60:61], v[18:19]
	v_lshl_add_u64 v[78:79], v[52:53], 0, v[78:79]
	v_pk_fma_f32 v[66:67], v[20:21], v[66:67], v[12:13]
	v_pk_fma_f32 v[60:61], v[2:3], v[8:9], v[60:61]
	v_pk_fma_f32 v[66:67], v[32:33], v[62:63], v[66:67]
	v_pk_fma_f32 v[60:61], v[6:7], v[36:37], v[60:61]
	v_pk_fma_f32 v[66:67], v[0:1], v[72:73], v[66:67]
	v_pk_fma_f32 v[60:61], v[10:11], v[58:59], v[60:61]
	v_pk_fma_f32 v[66:67], v[24:25], v[68:69], v[66:67]
	v_bfe_u32 v45, v60, 16, 1
	v_bfe_u32 v55, v89, 16, 1
	v_bfe_u32 v5, v61, 16, 1
	v_bfe_u32 v90, v88, 16, 1
	v_add3_u32 v55, v89, v55, s27
	v_add3_u32 v45, v60, v45, s27
	v_bfe_u32 v60, v76, 16, 1
	v_bfe_u32 v89, v66, 16, 1
	v_add3_u32 v88, v88, v90, s27
	v_add3_u32 v5, v61, v5, s27
	v_bfe_u32 v61, v77, 16, 1
	v_bfe_u32 v90, v67, 16, 1
	v_add3_u32 v66, v66, v89, s27
	v_add3_u32 v60, v76, v60, s27
	v_add3_u32 v67, v67, v90, s27
	v_add3_u32 v61, v77, v61, s27
	v_lshrrev_b32_e32 v60, 16, v60
	v_lshrrev_b32_e32 v66, 16, v66
	v_lshrrev_b32_e32 v61, 16, v61
	v_lshrrev_b32_e32 v67, 16, v67
	v_and_or_b32 v90, v45, s26, v66
	v_and_or_b32 v88, v88, s26, v60
	s_waitcnt vmcnt(8)
	v_lshlrev_b32_e32 v66, 16, v180
	v_and_b32_e32 v60, 0xffff0000, v180
	v_or_b32_e32 v84, 9, v54
	v_and_or_b32 v91, v5, s26, v67
	v_and_or_b32 v89, v55, s26, v61
	v_lshlrev_b32_e32 v67, 16, v181
	v_and_b32_e32 v61, 0xffff0000, v181
	v_ashrrev_i32_e32 v85, 31, v84
	v_pk_fma_f32 v[64:65], v[46:47], v[64:65], v[50:51]
	v_pk_fma_f32 v[16:17], v[34:35], v[16:17], v[38:39]
	v_lshl_add_u64 v[84:85], s[42:43], 0, v[84:85]
	v_pk_fma_f32 v[64:65], v[48:49], v[74:75], v[64:65]
	v_pk_fma_f32 v[16:17], v[22:23], v[28:29], v[16:17]
	v_lshlrev_b64 v[84:85], 11, v[84:85]
	v_pk_fma_f32 v[64:65], v[40:41], v[70:71], v[64:65]
	v_pk_fma_f32 v[16:17], v[26:27], v[42:43], v[16:17]
	v_lshl_add_u64 v[84:85], v[52:53], 0, v[84:85]
	ds_write_b128 v4, v[88:91] offset:3168
	v_pk_fma_f32 v[76:77], v[56:57], v[66:67], v[64:65]
	v_pk_fma_f32 v[88:89], v[30:31], v[60:61], v[16:17]
	v_lshlrev_b32_e32 v65, 16, v183
	v_lshlrev_b32_e32 v64, 16, v182
	v_and_b32_e32 v17, 0xffff0000, v183
	v_and_b32_e32 v16, 0xffff0000, v182
	v_pk_fma_f32 v[62:63], v[20:21], v[62:63], v[12:13]
	v_pk_fma_f32 v[8:9], v[14:15], v[8:9], v[18:19]
	v_pk_fma_f32 v[62:63], v[32:33], v[72:73], v[62:63]
	v_pk_fma_f32 v[8:9], v[2:3], v[36:37], v[8:9]
	v_pk_fma_f32 v[62:63], v[0:1], v[68:69], v[62:63]
	v_pk_fma_f32 v[8:9], v[6:7], v[58:59], v[8:9]
	v_pk_fma_f32 v[62:63], v[24:25], v[64:65], v[62:63]
	v_bfe_u32 v55, v89, 16, 1
	v_pk_fma_f32 v[8:9], v[10:11], v[16:17], v[8:9]
	v_bfe_u32 v90, v88, 16, 1
	v_add3_u32 v55, v89, v55, s27
	v_bfe_u32 v89, v62, 16, 1
	v_bfe_u32 v5, v9, 16, 1
	v_bfe_u32 v45, v8, 16, 1
	v_add3_u32 v88, v88, v90, s27
	v_bfe_u32 v90, v63, 16, 1
	v_add3_u32 v62, v62, v89, s27
	v_add3_u32 v8, v8, v45, s27
	v_add3_u32 v5, v9, v5, s27
	v_bfe_u32 v9, v76, 16, 1
	v_add3_u32 v63, v63, v90, s27
	v_lshrrev_b32_e32 v62, 16, v62
	v_bfe_u32 v45, v77, 16, 1
	v_add3_u32 v9, v76, v9, s27
	v_lshrrev_b32_e32 v63, 16, v63
	v_and_or_b32 v90, v8, s26, v62
	v_add3_u32 v45, v77, v45, s27
	s_waitcnt vmcnt(7)
	v_lshlrev_b32_e32 v76, 16, v184
	v_and_b32_e32 v62, 0xffff0000, v184
	v_or_b32_e32 v78, 10, v54
	v_and_or_b32 v91, v5, s26, v63
	v_lshlrev_b32_e32 v77, 16, v185
	v_and_b32_e32 v63, 0xffff0000, v185
	v_ashrrev_i32_e32 v79, 31, v78
	v_pk_fma_f32 v[28:29], v[34:35], v[28:29], v[38:39]
	v_lshl_add_u64 v[78:79], s[42:43], 0, v[78:79]
	v_lshrrev_b32_e32 v9, 16, v9
	v_lshrrev_b32_e32 v45, 16, v45
	v_pk_fma_f32 v[28:29], v[22:23], v[42:43], v[28:29]
	v_lshlrev_b64 v[78:79], 11, v[78:79]
	v_and_or_b32 v89, v55, s26, v45
	v_and_or_b32 v88, v88, s26, v9
	v_pk_fma_f32 v[28:29], v[26:27], v[60:61], v[28:29]
	v_lshl_add_u64 v[78:79], v[52:53], 0, v[78:79]
	ds_write_b128 v4, v[88:91] offset:3696
	v_pk_fma_f32 v[8:9], v[46:47], v[74:75], v[50:51]
	v_pk_fma_f32 v[88:89], v[30:31], v[62:63], v[28:29]
	v_lshlrev_b32_e32 v75, 16, v187
	v_lshlrev_b32_e32 v74, 16, v186
	v_and_b32_e32 v29, 0xffff0000, v187
	v_and_b32_e32 v28, 0xffff0000, v186
	v_pk_fma_f32 v[72:73], v[20:21], v[72:73], v[12:13]
	v_pk_fma_f32 v[36:37], v[14:15], v[36:37], v[18:19]
	v_pk_fma_f32 v[72:73], v[32:33], v[68:69], v[72:73]
	v_pk_fma_f32 v[36:37], v[2:3], v[58:59], v[36:37]
	v_pk_fma_f32 v[8:9], v[48:49], v[70:71], v[8:9]
	v_pk_fma_f32 v[72:73], v[0:1], v[64:65], v[72:73]
	v_pk_fma_f32 v[36:37], v[6:7], v[16:17], v[36:37]
	v_pk_fma_f32 v[8:9], v[40:41], v[66:67], v[8:9]
	v_pk_fma_f32 v[72:73], v[24:25], v[74:75], v[72:73]
	v_pk_fma_f32 v[36:37], v[10:11], v[28:29], v[36:37]
	v_bfe_u32 v55, v89, 16, 1
	v_pk_fma_f32 v[8:9], v[56:57], v[76:77], v[8:9]
	v_bfe_u32 v5, v37, 16, 1
	v_add3_u32 v55, v89, v55, s27
	v_bfe_u32 v89, v72, 16, 1
	v_bfe_u32 v45, v36, 16, 1
	v_bfe_u32 v90, v88, 16, 1
	v_add3_u32 v5, v37, v5, s27
	v_bfe_u32 v37, v8, 16, 1
	v_add3_u32 v72, v72, v89, s27
	v_add3_u32 v88, v88, v90, s27
	v_add3_u32 v36, v36, v45, s27
	v_bfe_u32 v90, v73, 16, 1
	v_add3_u32 v8, v8, v37, s27
	v_lshrrev_b32_e32 v37, 16, v72
	v_bfe_u32 v45, v9, 16, 1
	v_add3_u32 v73, v73, v90, s27
	v_and_or_b32 v90, v36, s26, v37
	s_waitcnt vmcnt(6)
	v_lshlrev_b32_e32 v72, 16, v188
	v_and_b32_e32 v36, 0xffff0000, v188
	v_or_b32_e32 v84, 11, v54
	v_add3_u32 v9, v9, v45, s27
	v_lshrrev_b32_e32 v45, 16, v73
	v_lshlrev_b32_e32 v73, 16, v189
	v_and_b32_e32 v37, 0xffff0000, v189
	v_ashrrev_i32_e32 v85, 31, v84
	v_pk_fma_f32 v[42:43], v[34:35], v[42:43], v[38:39]
	v_lshl_add_u64 v[84:85], s[42:43], 0, v[84:85]
	v_lshrrev_b32_e32 v8, 16, v8
	v_lshrrev_b32_e32 v9, 16, v9
	v_pk_fma_f32 v[42:43], v[22:23], v[60:61], v[42:43]
	v_lshlrev_b64 v[84:85], 11, v[84:85]
	v_and_or_b32 v91, v5, s26, v45
	v_and_or_b32 v89, v55, s26, v9
	v_and_or_b32 v88, v88, s26, v8
	v_pk_fma_f32 v[42:43], v[26:27], v[62:63], v[42:43]
	v_lshl_add_u64 v[84:85], v[52:53], 0, v[84:85]
	ds_write_b128 v4, v[88:91] offset:4224
	v_pk_fma_f32 v[8:9], v[46:47], v[70:71], v[50:51]
	v_pk_fma_f32 v[88:89], v[30:31], v[36:37], v[42:43]
	v_lshlrev_b32_e32 v71, 16, v191
	v_lshlrev_b32_e32 v70, 16, v190
	v_and_b32_e32 v43, 0xffff0000, v191
	v_and_b32_e32 v42, 0xffff0000, v190
	v_pk_fma_f32 v[58:59], v[14:15], v[58:59], v[18:19]
	v_pk_fma_f32 v[8:9], v[48:49], v[66:67], v[8:9]
	v_pk_fma_f32 v[58:59], v[2:3], v[16:17], v[58:59]
	v_pk_fma_f32 v[68:69], v[20:21], v[68:69], v[12:13]
	v_pk_fma_f32 v[58:59], v[6:7], v[28:29], v[58:59]
	v_pk_fma_f32 v[8:9], v[40:41], v[76:77], v[8:9]
	v_pk_fma_f32 v[68:69], v[32:33], v[64:65], v[68:69]
	v_pk_fma_f32 v[58:59], v[10:11], v[42:43], v[58:59]
	v_pk_fma_f32 v[8:9], v[56:57], v[72:73], v[8:9]
	v_pk_fma_f32 v[68:69], v[0:1], v[74:75], v[68:69]
	v_bfe_u32 v5, v59, 16, 1
	v_bfe_u32 v45, v58, 16, 1
	v_pk_fma_f32 v[68:69], v[24:25], v[70:71], v[68:69]
	v_bfe_u32 v55, v89, 16, 1
	v_add3_u32 v45, v58, v45, s27
	v_add3_u32 v5, v59, v5, s27
	v_bfe_u32 v58, v8, 16, 1
	v_bfe_u32 v59, v9, 16, 1
	v_bfe_u32 v90, v88, 16, 1
	v_add3_u32 v55, v89, v55, s27
	v_bfe_u32 v89, v68, 16, 1
	v_add3_u32 v9, v9, v59, s27
	v_add3_u32 v8, v8, v58, s27
	v_add3_u32 v88, v88, v90, s27
	v_bfe_u32 v90, v69, 16, 1
	v_add3_u32 v68, v68, v89, s27
	v_lshrrev_b32_e32 v8, 16, v8
	v_lshrrev_b32_e32 v9, 16, v9
	v_add3_u32 v69, v69, v90, s27
	v_lshrrev_b32_e32 v58, 16, v68
	v_and_or_b32 v89, v55, s26, v9
	v_and_or_b32 v88, v88, s26, v8
	v_pk_fma_f32 v[8:9], v[46:47], v[66:67], v[50:51]
	v_lshrrev_b32_e32 v59, 16, v69
	v_and_or_b32 v90, v45, s26, v58
	s_waitcnt vmcnt(5)
	v_lshlrev_b32_e32 v68, 16, v192
	v_and_b32_e32 v58, 0xffff0000, v192
	v_pk_fma_f32 v[8:9], v[48:49], v[76:77], v[8:9]
	v_or_b32_e32 v78, 12, v54
	v_and_or_b32 v91, v5, s26, v59
	v_lshlrev_b32_e32 v69, 16, v193
	v_and_b32_e32 v59, 0xffff0000, v193
	v_pk_fma_f32 v[8:9], v[40:41], v[72:73], v[8:9]
	v_ashrrev_i32_e32 v79, 31, v78
	ds_write_b128 v4, v[88:91] offset:4752
	v_pk_fma_f32 v[88:89], v[56:57], v[68:69], v[8:9]
	v_pk_fma_f32 v[8:9], v[34:35], v[60:61], v[38:39]
	v_lshl_add_u64 v[78:79], s[42:43], 0, v[78:79]
	v_pk_fma_f32 v[8:9], v[22:23], v[62:63], v[8:9]
	v_pk_fma_f32 v[16:17], v[14:15], v[16:17], v[18:19]
	v_lshlrev_b64 v[78:79], 11, v[78:79]
	v_pk_fma_f32 v[8:9], v[26:27], v[36:37], v[8:9]
	v_pk_fma_f32 v[64:65], v[20:21], v[64:65], v[12:13]
	v_pk_fma_f32 v[16:17], v[2:3], v[28:29], v[16:17]
	v_lshl_add_u64 v[78:79], v[52:53], 0, v[78:79]
	v_pk_fma_f32 v[60:61], v[30:31], v[58:59], v[8:9]
	v_lshlrev_b32_e32 v67, 16, v195
	v_lshlrev_b32_e32 v66, 16, v194
	v_and_b32_e32 v9, 0xffff0000, v195
	v_and_b32_e32 v8, 0xffff0000, v194
	v_pk_fma_f32 v[64:65], v[32:33], v[74:75], v[64:65]
	v_pk_fma_f32 v[16:17], v[6:7], v[42:43], v[16:17]
	v_pk_fma_f32 v[64:65], v[0:1], v[70:71], v[64:65]
	v_pk_fma_f32 v[16:17], v[10:11], v[8:9], v[16:17]
	v_pk_fma_f32 v[64:65], v[24:25], v[66:67], v[64:65]
	v_bfe_u32 v5, v17, 16, 1
	v_bfe_u32 v55, v61, 16, 1
	v_bfe_u32 v90, v60, 16, 1
	v_add3_u32 v55, v61, v55, s27
	v_add3_u32 v5, v17, v5, s27
	v_bfe_u32 v17, v88, 16, 1
	v_bfe_u32 v61, v64, 16, 1
	v_bfe_u32 v45, v16, 16, 1
	v_add3_u32 v60, v60, v90, s27
	v_bfe_u32 v90, v65, 16, 1
	v_add3_u32 v61, v64, v61, s27
	v_add3_u32 v17, v88, v17, s27
	v_add3_u32 v16, v16, v45, s27
	v_add3_u32 v65, v65, v90, s27
	v_lshrrev_b32_e32 v17, 16, v17
	v_lshrrev_b32_e32 v61, 16, v61
	v_lshrrev_b32_e32 v64, 16, v65
	v_and_or_b32 v90, v16, s26, v61
	v_and_or_b32 v88, v60, s26, v17
	v_pk_fma_f32 v[60:61], v[46:47], v[76:77], v[50:51]
	v_and_or_b32 v91, v5, s26, v64
	s_waitcnt vmcnt(4)
	v_lshlrev_b32_e32 v64, 16, v196
	v_and_b32_e32 v16, 0xffff0000, v196
	v_pk_fma_f32 v[60:61], v[48:49], v[72:73], v[60:61]
	v_or_b32_e32 v84, 13, v54
	v_bfe_u32 v45, v89, 16, 1
	v_lshlrev_b32_e32 v65, 16, v197
	v_and_b32_e32 v17, 0xffff0000, v197
	v_pk_fma_f32 v[60:61], v[40:41], v[68:69], v[60:61]
	v_ashrrev_i32_e32 v85, 31, v84
	v_add3_u32 v45, v89, v45, s27
	v_pk_fma_f32 v[76:77], v[56:57], v[64:65], v[60:61]
	v_pk_fma_f32 v[60:61], v[34:35], v[62:63], v[38:39]
	v_lshl_add_u64 v[84:85], s[42:43], 0, v[84:85]
	v_lshrrev_b32_e32 v45, 16, v45
	v_pk_fma_f32 v[60:61], v[22:23], v[36:37], v[60:61]
	v_lshlrev_b64 v[84:85], 11, v[84:85]
	v_and_or_b32 v89, v55, s26, v45
	v_pk_fma_f32 v[60:61], v[26:27], v[58:59], v[60:61]
	v_lshl_add_u64 v[84:85], v[52:53], 0, v[84:85]
	ds_write_b128 v4, v[88:91] offset:5280
	v_pk_fma_f32 v[88:89], v[30:31], v[16:17], v[60:61]
	v_lshlrev_b32_e32 v63, 16, v199
	v_lshlrev_b32_e32 v62, 16, v198
	v_and_b32_e32 v61, 0xffff0000, v199
	v_and_b32_e32 v60, 0xffff0000, v198
	v_pk_fma_f32 v[28:29], v[14:15], v[28:29], v[18:19]
	v_pk_fma_f32 v[74:75], v[20:21], v[74:75], v[12:13]
	v_pk_fma_f32 v[28:29], v[2:3], v[42:43], v[28:29]
	v_pk_fma_f32 v[74:75], v[32:33], v[70:71], v[74:75]
	v_pk_fma_f32 v[28:29], v[6:7], v[8:9], v[28:29]
	v_pk_fma_f32 v[74:75], v[0:1], v[66:67], v[74:75]
	v_pk_fma_f32 v[28:29], v[10:11], v[60:61], v[28:29]
	v_pk_fma_f32 v[74:75], v[24:25], v[62:63], v[74:75]
	v_bfe_u32 v5, v29, 16, 1
	v_bfe_u32 v55, v89, 16, 1
	v_bfe_u32 v45, v28, 16, 1
	v_bfe_u32 v90, v88, 16, 1
	v_add3_u32 v55, v89, v55, s27
	v_add3_u32 v5, v29, v5, s27
	v_bfe_u32 v29, v76, 16, 1
	v_bfe_u32 v89, v74, 16, 1
	v_add3_u32 v88, v88, v90, s27
	v_add3_u32 v28, v28, v45, s27
	v_bfe_u32 v45, v77, 16, 1
	v_bfe_u32 v90, v75, 16, 1
	v_add3_u32 v74, v74, v89, s27
	v_add3_u32 v29, v76, v29, s27
	v_add3_u32 v75, v75, v90, s27
	v_add3_u32 v45, v77, v45, s27
	v_lshrrev_b32_e32 v29, 16, v29
	v_lshrrev_b32_e32 v74, 16, v74
	v_lshrrev_b32_e32 v45, 16, v45
	v_lshrrev_b32_e32 v75, 16, v75
	v_and_or_b32 v76, v28, s26, v74
	v_and_or_b32 v74, v88, s26, v29
	v_pk_fma_f32 v[28:29], v[46:47], v[72:73], v[50:51]
	v_and_or_b32 v77, v5, s26, v75
	v_and_or_b32 v75, v55, s26, v45
	v_pk_fma_f32 v[28:29], v[48:49], v[68:69], v[28:29]
	ds_write_b128 v4, v[74:77] offset:5808
	s_waitcnt vmcnt(3)
	v_lshlrev_b32_e32 v77, 16, v201
	v_lshlrev_b32_e32 v76, 16, v200
	v_pk_fma_f32 v[28:29], v[40:41], v[64:65], v[28:29]
	v_and_b32_e32 v75, 0xffff0000, v201
	v_and_b32_e32 v74, 0xffff0000, v200
	v_pk_fma_f32 v[78:79], v[56:57], v[76:77], v[28:29]
	v_pk_fma_f32 v[28:29], v[34:35], v[36:37], v[38:39]
	v_or_b32_e32 v54, 14, v54
	v_pk_fma_f32 v[28:29], v[22:23], v[58:59], v[28:29]
	v_pk_fma_f32 v[42:43], v[14:15], v[42:43], v[18:19]
	v_ashrrev_i32_e32 v55, 31, v54
	v_pk_fma_f32 v[28:29], v[26:27], v[16:17], v[28:29]
	v_pk_fma_f32 v[70:71], v[20:21], v[70:71], v[12:13]
	v_pk_fma_f32 v[42:43], v[2:3], v[8:9], v[42:43]
	v_lshl_add_u64 v[54:55], s[42:43], 0, v[54:55]
	v_pk_fma_f32 v[88:89], v[30:31], v[74:75], v[28:29]
	v_and_b32_e32 v29, 0xffff0000, v203
	v_and_b32_e32 v28, 0xffff0000, v202
	v_pk_fma_f32 v[70:71], v[32:33], v[66:67], v[70:71]
	v_pk_fma_f32 v[42:43], v[6:7], v[60:61], v[42:43]
	v_lshlrev_b64 v[54:55], 11, v[54:55]
	v_lshlrev_b32_e32 v37, 16, v203
	v_lshlrev_b32_e32 v36, 16, v202
	v_pk_fma_f32 v[70:71], v[0:1], v[62:63], v[70:71]
	v_pk_fma_f32 v[42:43], v[10:11], v[28:29], v[42:43]
	v_lshl_add_u64 v[54:55], v[52:53], 0, v[54:55]
	v_pk_fma_f32 v[80:81], v[24:25], v[36:37], v[70:71]
	v_bfe_u32 v5, v43, 16, 1
	v_bfe_u32 v45, v42, 16, 1
	v_bfe_u32 v54, v89, 16, 1
	v_bfe_u32 v55, v88, 16, 1
	v_add3_u32 v55, v88, v55, s27
	v_add3_u32 v54, v89, v54, s27
	v_add3_u32 v42, v42, v45, s27
	v_add3_u32 v5, v43, v5, s27
	v_bfe_u32 v43, v78, 16, 1
	v_bfe_u32 v45, v79, 16, 1
	v_bfe_u32 v88, v80, 16, 1
	v_bfe_u32 v89, v81, 16, 1
	v_add3_u32 v81, v81, v89, s27
	v_add3_u32 v80, v80, v88, s27
	v_add3_u32 v45, v79, v45, s27
	v_add3_u32 v43, v78, v43, s27
	v_lshrrev_b32_e32 v43, 16, v43
	v_lshrrev_b32_e32 v45, 16, v45
	v_lshrrev_b32_e32 v78, 16, v80
	v_lshrrev_b32_e32 v79, 16, v81
	v_and_or_b32 v81, v5, s26, v79
	v_and_or_b32 v80, v42, s26, v78
	v_and_or_b32 v79, v54, s26, v45
	v_and_or_b32 v78, v55, s26, v43
	v_pk_fma_f32 v[54:55], v[46:47], v[68:69], v[50:51]
	s_waitcnt vmcnt(2)
	v_lshlrev_b32_e32 v43, 16, v205
	v_pk_fma_f32 v[54:55], v[48:49], v[64:65], v[54:55]
	v_lshlrev_b32_e32 v42, 16, v204
	v_pk_fma_f32 v[54:55], v[40:41], v[76:77], v[54:55]
	ds_write_b128 v4, v[78:81] offset:6336
	v_pk_fma_f32 v[68:69], v[56:57], v[42:43], v[54:55]
	v_pk_fma_f32 v[54:55], v[34:35], v[58:59], v[38:39]
	v_and_b32_e32 v79, 0xffff0000, v205
	v_pk_fma_f32 v[54:55], v[22:23], v[16:17], v[54:55]
	v_and_b32_e32 v78, 0xffff0000, v204
	v_pk_fma_f32 v[54:55], v[26:27], v[74:75], v[54:55]
	v_lshlrev_b32_e32 v80, 16, v206
	v_pk_fma_f32 v[58:59], v[30:31], v[78:79], v[54:55]
	v_and_b32_e32 v84, 0xffff0000, v206
	v_pk_fma_f32 v[54:55], v[20:21], v[66:67], v[12:13]
	v_or_b32_e32 v86, 15, v83
	v_lshlrev_b32_e32 v81, 16, v207
	v_and_b32_e32 v85, 0xffff0000, v207
	v_pk_fma_f32 v[54:55], v[32:33], v[62:63], v[54:55]
	v_ashrrev_i32_e32 v87, 31, v86
	v_pk_fma_f32 v[66:67], v[0:1], v[36:37], v[54:55]
	v_lshl_add_u64 v[54:55], s[42:43], 0, v[86:87]
	v_lshlrev_b64 v[54:55], 11, v[54:55]
	v_lshl_add_u64 v[52:53], v[52:53], 0, v[54:55]
	v_pk_fma_f32 v[8:9], v[14:15], v[8:9], v[18:19]
	v_pk_fma_f32 v[66:67], v[24:25], v[80:81], v[66:67]
	v_pk_fma_f32 v[8:9], v[2:3], v[60:61], v[8:9]
	v_bfe_u32 v83, v59, 16, 1
	v_pk_fma_f32 v[8:9], v[6:7], v[28:29], v[8:9]
	v_bfe_u32 v87, v58, 16, 1
	v_pk_fma_f32 v[8:9], v[10:11], v[84:85], v[8:9]
	v_add3_u32 v58, v58, v87, s27
	v_bfe_u32 v5, v9, 16, 1
	v_bfe_u32 v45, v8, 16, 1
	v_add3_u32 v59, v59, v83, s27
	v_add3_u32 v8, v8, v45, s27
	v_add3_u32 v5, v9, v5, s27
	v_bfe_u32 v9, v68, 16, 1
	v_bfe_u32 v45, v69, 16, 1
	v_bfe_u32 v83, v66, 16, 1
	v_bfe_u32 v87, v67, 16, 1
	v_add3_u32 v67, v67, v87, s27
	v_add3_u32 v66, v66, v83, s27
	v_add3_u32 v45, v69, v45, s27
	v_add3_u32 v9, v68, v9, s27
	v_lshrrev_b32_e32 v9, 16, v9
	v_lshrrev_b32_e32 v45, 16, v45
	v_lshrrev_b32_e32 v66, 16, v66
	v_lshrrev_b32_e32 v67, 16, v67
	v_pk_fma_f32 v[16:17], v[34:35], v[16:17], v[38:39]
	v_pk_fma_f32 v[60:61], v[14:15], v[60:61], v[18:19]
	v_and_or_b32 v69, v5, s26, v67
	v_and_or_b32 v68, v8, s26, v66
	v_and_or_b32 v67, v59, s26, v45
	v_and_or_b32 v66, v58, s26, v9
	v_pk_fma_f32 v[58:59], v[46:47], v[64:65], v[50:51]
	v_pk_fma_f32 v[16:17], v[22:23], v[74:75], v[16:17]
	v_pk_fma_f32 v[62:63], v[20:21], v[62:63], v[12:13]
	v_pk_fma_f32 v[60:61], v[2:3], v[28:29], v[60:61]
	ds_write_b128 v4, v[66:69] offset:6864
	s_waitcnt vmcnt(1)
	v_and_b32_e32 v67, 0xffff0000, v209
	v_and_b32_e32 v66, 0xffff0000, v208
	v_pk_fma_f32 v[58:59], v[48:49], v[76:77], v[58:59]
	v_pk_fma_f32 v[16:17], v[26:27], v[78:79], v[16:17]
	v_and_b32_e32 v69, 0xffff0000, v211
	v_and_b32_e32 v68, 0xffff0000, v210
	v_pk_fma_f32 v[62:63], v[32:33], v[36:37], v[62:63]
	v_pk_fma_f32 v[60:61], v[6:7], v[84:85], v[60:61]
	v_lshlrev_b32_e32 v9, 16, v209
	v_lshlrev_b32_e32 v8, 16, v208
	v_pk_fma_f32 v[58:59], v[40:41], v[42:43], v[58:59]
	v_pk_fma_f32 v[16:17], v[30:31], v[66:67], v[16:17]
	v_lshlrev_b32_e32 v65, 16, v211
	v_lshlrev_b32_e32 v64, 16, v210
	v_pk_fma_f32 v[62:63], v[0:1], v[80:81], v[62:63]
	v_pk_fma_f32 v[60:61], v[10:11], v[68:69], v[60:61]
	v_pk_fma_f32 v[58:59], v[56:57], v[8:9], v[58:59]
	v_pk_fma_f32 v[62:63], v[24:25], v[64:65], v[62:63]
	v_bfe_u32 v5, v61, 16, 1
	v_bfe_u32 v45, v60, 16, 1
	v_bfe_u32 v70, v17, 16, 1
	v_bfe_u32 v71, v16, 16, 1
	v_add3_u32 v16, v16, v71, s27
	v_add3_u32 v17, v17, v70, s27
	v_add3_u32 v45, v60, v45, s27
	v_add3_u32 v5, v61, v5, s27
	v_bfe_u32 v60, v58, 16, 1
	v_bfe_u32 v61, v59, 16, 1
	v_bfe_u32 v70, v62, 16, 1
	v_bfe_u32 v71, v63, 16, 1
	v_add3_u32 v63, v63, v71, s27
	v_add3_u32 v62, v62, v70, s27
	v_add3_u32 v59, v59, v61, s27
	v_add3_u32 v58, v58, v60, s27
	v_lshrrev_b32_e32 v58, 16, v58
	v_lshrrev_b32_e32 v59, 16, v59
	v_lshrrev_b32_e32 v60, 16, v62
	v_lshrrev_b32_e32 v61, 16, v63
	v_pk_fma_f32 v[46:47], v[46:47], v[76:77], v[50:51]
	v_and_or_b32 v61, v5, s26, v61
	v_and_or_b32 v60, v45, s26, v60
	v_and_or_b32 v59, v17, s26, v59
	v_and_or_b32 v58, v16, s26, v58
	v_pk_fma_f32 v[42:43], v[48:49], v[42:43], v[46:47]
	v_pk_fma_f32 v[12:13], v[20:21], v[36:37], v[12:13]
	ds_write_b128 v4, v[92:95]
	ds_write_b128 v4, v[58:61] offset:7392
	s_waitcnt vmcnt(0)
	v_lshlrev_b32_e32 v5, 16, v213
	v_lshlrev_b32_e32 v4, 16, v212
	v_pk_fma_f32 v[8:9], v[40:41], v[8:9], v[42:43]
	v_pk_fma_f32 v[12:13], v[32:33], v[80:81], v[12:13]
	v_pk_fma_f32 v[4:5], v[56:57], v[4:5], v[8:9]
	v_pk_fma_f32 v[8:9], v[34:35], v[74:75], v[38:39]
	v_pk_fma_f32 v[0:1], v[0:1], v[64:65], v[12:13]
	v_pk_fma_f32 v[12:13], v[14:15], v[28:29], v[18:19]
	v_pk_fma_f32 v[8:9], v[22:23], v[78:79], v[8:9]
	v_pk_fma_f32 v[2:3], v[2:3], v[84:85], v[12:13]
	v_and_b32_e32 v17, 0xffff0000, v213
	v_and_b32_e32 v16, 0xffff0000, v212
	v_pk_fma_f32 v[8:9], v[26:27], v[66:67], v[8:9]
	v_and_b32_e32 v23, 0xffff0000, v215
	v_and_b32_e32 v22, 0xffff0000, v214
	v_pk_fma_f32 v[2:3], v[6:7], v[68:69], v[2:3]
	v_pk_fma_f32 v[8:9], v[30:31], v[16:17], v[8:9]
	v_lshlrev_b32_e32 v17, 16, v215
	v_lshlrev_b32_e32 v16, 16, v214
	v_pk_fma_f32 v[2:3], v[10:11], v[22:23], v[2:3]
	v_pk_fma_f32 v[0:1], v[24:25], v[16:17], v[0:1]
	v_bfe_u32 v6, v3, 16, 1
	v_bfe_u32 v7, v2, 16, 1
	v_bfe_u32 v10, v9, 16, 1
	v_bfe_u32 v11, v8, 16, 1
	v_add3_u32 v8, v8, v11, s27
	v_add3_u32 v9, v9, v10, s27
	v_add3_u32 v2, v2, v7, s27
	v_add3_u32 v3, v3, v6, s27
	v_bfe_u32 v6, v4, 16, 1
	v_bfe_u32 v7, v5, 16, 1
	v_bfe_u32 v10, v0, 16, 1
	v_bfe_u32 v11, v1, 16, 1
	v_add3_u32 v1, v1, v11, s27
	v_add3_u32 v0, v0, v10, s27
	v_add3_u32 v5, v5, v7, s27
	v_add3_u32 v4, v4, v6, s27
	v_lshrrev_b32_e32 v4, 16, v4
	v_lshrrev_b32_e32 v5, 16, v5
	v_lshrrev_b32_e32 v0, 16, v0
	v_lshrrev_b32_e32 v1, 16, v1
	v_and_or_b32 v3, v3, s26, v1
	v_and_or_b32 v2, v2, s26, v0
	v_and_or_b32 v1, v9, s26, v5
	v_and_or_b32 v0, v8, s26, v4
	v_mad_u64_u32 v[4:5], s[0:1], v86, s30, v[44:45]
	s_and_b32 s0, s19, 0xffffffe0
	ds_write_b128 v4, v[0:3]
	v_and_b32_e32 v0, 31, v82
	s_add_i32 s0, s0, s18
	v_or_b32_e32 v104, s0, v0
	s_ashr_i32 s0, s0, 7
	s_ashr_i32 s1, s0, 31
	s_lshl_b64 s[0:1], s[0:1], 16
	v_lshlrev_b32_e32 v1, 8, v104
	s_add_u32 s0, s40, s0
	v_and_b32_e32 v100, 0x7f00, v1
	s_addc_u32 s1, s41, s1
	v_lshl_add_u64 v[2:3], s[0:1], 0, v[100:101]
	v_lshlrev_b32_e32 v100, 4, v96
	v_lshl_add_u64 v[2:3], v[2:3], 0, v[100:101]
	s_waitcnt lgkmcnt(0)
	s_barrier
	v_lshl_add_u64 v[4:5], v[2:3], 0, s[10:11]
	global_load_dwordx4 v[32:35], v[2:3], off
	global_load_dwordx4 v[36:39], v[2:3], off offset:32
	global_load_dwordx4 v[40:43], v[4:5], off offset:32
	global_load_dwordx4 v[44:47], v[4:5], off offset:64
	global_load_dwordx4 v[48:51], v[2:3], off offset:64
	global_load_dwordx4 v[52:55], v[2:3], off offset:96
	global_load_dwordx4 v[56:59], v[4:5], off offset:96
	global_load_dwordx4 v[60:63], v[4:5], off offset:128
	global_load_dwordx4 v[64:67], v[2:3], off offset:128
	global_load_dwordx4 v[68:71], v[2:3], off offset:160
	global_load_dwordx4 v[72:75], v[4:5], off offset:160
	global_load_dwordx4 v[76:79], v[4:5], off offset:192
	global_load_dwordx4 v[80:83], v[2:3], off offset:192
	global_load_dwordx4 v[84:87], v[2:3], off offset:224
	v_ashrrev_i32_e32 v105, 31, v104
	v_add_co_u32_e32 v6, vcc, s31, v2
	v_lshlrev_b64 v[8:9], 2, v[104:105]
	s_nop 0
	v_addc_co_u32_e32 v7, vcc, 0, v3, vcc
	v_lshl_add_u64 v[2:3], s[70:71], 0, v[8:9]
	global_load_dword v10, v[2:3], off
	global_load_dwordx4 v[88:91], v[6:7], off
	global_load_dwordx4 v[92:95], v[4:5], off offset:224
	v_lshl_add_u64 v[2:3], s[64:65], 0, v[8:9]
	v_lshl_add_u64 v[4:5], s[68:69], 0, v[8:9]
	global_load_dword v2, v[2:3], off
	s_waitcnt vmcnt(3)
	v_mul_f32_e32 v3, 0xbfb8aa3b, v10
	global_load_dword v1, v[4:5], off
	v_exp_f32_e32 v3, v3
	v_cmp_nlt_f32_e32 vcc, s33, v10
	s_and_saveexec_b64 s[0:1], vcc
	s_cbranch_execz .LBB0_391
	v_add_f32_e32 v6, 1.0, v3
	v_add_f32_e32 v4, -1.0, v6
	v_sub_f32_e32 v5, v4, v6
	v_add_f32_e32 v5, 1.0, v5
	v_sub_f32_e32 v4, v3, v4
	v_add_f32_e32 v7, v4, v5
	v_frexp_mant_f32_e32 v8, v6
	v_cvt_f64_f32_e32 v[4:5], v6
	v_frexp_exp_i32_f64_e32 v4, v[4:5]
	v_cmp_gt_f32_e32 vcc, s34, v8
	s_nop 1
	v_subbrev_co_u32_e32 v12, vcc, 0, v4, vcc
	v_sub_u32_e32 v4, 0, v12
	v_ldexp_f32 v5, v6, v4
	v_add_f32_e32 v6, -1.0, v5
	v_add_f32_e32 v8, 1.0, v5
	v_ldexp_f32 v4, v7, v4
	v_add_f32_e32 v7, 1.0, v6
	v_add_f32_e32 v9, -1.0, v8
	v_sub_f32_e32 v7, v5, v7
	v_sub_f32_e32 v5, v5, v9
	v_add_f32_e32 v7, v4, v7
	v_add_f32_e32 v4, v4, v5
	v_add_f32_e32 v13, v8, v4
	v_rcp_f32_e32 v15, v13
	v_sub_f32_e32 v5, v13, v8
	v_sub_f32_e32 v14, v4, v5
	v_add_f32_e32 v5, v6, v7
	v_mul_f32_e32 v17, v5, v15
	v_sub_f32_e32 v4, v5, v6
	v_mul_f32_e32 v6, v13, v17
	v_fma_f32 v8, v17, v13, -v6
	v_fmac_f32_e32 v8, v17, v14
	v_sub_f32_e32 v16, v7, v4
	v_add_f32_e32 v4, v6, v8
	v_sub_f32_e32 v7, v5, v4
	v_pk_add_f32 v[10:11], v[4:5], v[6:7] neg_lo:[0,1] neg_hi:[0,1]
	v_mov_b32_e32 v9, v4
	v_pk_add_f32 v[4:5], v[10:11], v[8:9] neg_lo:[0,1] neg_hi:[0,1]
	v_cmp_neq_f32_e32 vcc, s44, v3
	v_add_f32_e32 v5, v16, v5
	v_add_f32_e32 v4, v4, v5
	v_add_f32_e32 v5, v7, v4
	v_mul_f32_e32 v16, v15, v5
	v_mul_f32_e32 v6, v13, v16
	v_fma_f32 v8, v16, v13, -v6
	v_fmac_f32_e32 v8, v16, v14
	v_sub_f32_e32 v7, v7, v5
	v_add_f32_e32 v13, v4, v7
	v_add_f32_e32 v4, v6, v8
	v_sub_f32_e32 v7, v5, v4
	v_pk_add_f32 v[10:11], v[4:5], v[6:7] neg_lo:[0,1] neg_hi:[0,1]
	v_mov_b32_e32 v9, v4
	v_pk_add_f32 v[4:5], v[10:11], v[8:9] neg_lo:[0,1] neg_hi:[0,1]
	s_nop 0
	v_add_f32_e32 v5, v13, v5
	v_add_f32_e32 v4, v4, v5
	v_add_f32_e32 v5, v17, v16
	v_add_f32_e32 v4, v7, v4
	v_sub_f32_e32 v6, v5, v17
	v_mul_f32_e32 v4, v15, v4
	v_sub_f32_e32 v6, v16, v6
	v_add_f32_e32 v6, v6, v4
	v_add_f32_e32 v8, v5, v6
	v_mul_f32_e32 v9, v8, v8
	v_fmamk_f32 v4, v9, 0x3e9b6dac, v112
	v_fmaak_f32 v103, v9, v4, 0x3f2aaada
	v_cvt_f32_i32_e32 v4, v12
	v_sub_f32_e32 v5, v8, v5
	v_sub_f32_e32 v5, v6, v5
	v_ldexp_f32 v10, v5, 1
	v_mul_f32_e32 v5, v8, v9
	v_ldexp_f32 v7, v8, 1
	v_pk_mul_f32 v[8:9], v[4:5], v[102:103]
	s_nop 0
	v_fma_f32 v6, v4, s35, -v8
	v_fmac_f32_e32 v6, 0xb102e308, v4
	v_pk_add_f32 v[4:5], v[8:9], v[6:7]
	s_nop 0
	v_sub_f32_e32 v7, v5, v7
	v_sub_f32_e32 v7, v9, v7
	v_add_f32_e32 v11, v10, v7
	v_mov_b32_e32 v10, v8
	v_pk_add_f32 v[8:9], v[4:5], v[8:9] neg_lo:[0,1] neg_hi:[0,1]
	v_pk_add_f32 v[12:13], v[4:5], v[10:11]
	v_mov_b32_e32 v7, v4
	v_mov_b32_e32 v9, v13
	v_pk_add_f32 v[14:15], v[6:7], v[8:9] neg_lo:[0,1] neg_hi:[0,1]
	v_pk_add_f32 v[6:7], v[6:7], v[8:9]
	v_mov_b32_e32 v10, v11
	v_pk_add_f32 v[8:9], v[6:7], v[4:5] op_sel:[1,0] op_sel_hi:[0,1] neg_lo:[0,1] neg_hi:[0,1]
	v_pk_add_f32 v[16:17], v[12:13], v[8:9] op_sel_hi:[1,0] neg_lo:[0,1] neg_hi:[0,1]
	v_mov_b32_e32 v12, v13
	v_mov_b32_e32 v13, v7
	v_pk_mov_b32 v[8:9], v[4:5], v[8:9] op_sel:[1,0]
	v_mov_b32_e32 v11, v4
	v_pk_add_f32 v[8:9], v[12:13], v[8:9] neg_lo:[0,1] neg_hi:[0,1]
	v_mov_b32_e32 v16, v14
	v_pk_add_f32 v[4:5], v[10:11], v[8:9] neg_lo:[0,1] neg_hi:[0,1]
	v_mov_b32_e32 v15, v7
	v_pk_add_f32 v[8:9], v[16:17], v[4:5]
	s_nop 0
	v_pk_add_f32 v[10:11], v[8:9], v[8:9] op_sel:[0,1] op_sel_hi:[1,0]
	s_nop 0
	v_pk_add_f32 v[6:7], v[6:7], v[10:11] op_sel:[1,0] op_sel_hi:[0,1]
	v_mov_b32_e32 v9, v6
	v_pk_add_f32 v[12:13], v[8:9], v[14:15] neg_lo:[0,1] neg_hi:[0,1]
	v_mov_b32_e32 v5, v10
	v_sub_f32_e32 v7, v8, v12
	v_pk_add_f32 v[4:5], v[4:5], v[12:13] neg_lo:[0,1] neg_hi:[0,1]
	v_sub_f32_e32 v7, v14, v7
	v_add_f32_e32 v4, v4, v7
	v_add_f32_e32 v4, v4, v5
	v_add_f32_e32 v4, v6, v4
	v_cndmask_b32_e32 v4, v113, v4, vcc
	v_cmp_ngt_f32_e32 vcc, -1.0, v3
	s_nop 1
	v_cndmask_b32_e32 v4, v114, v4, vcc
	v_cmp_neq_f32_e32 vcc, -1.0, v3
	s_nop 1
	v_cndmask_b32_e32 v4, v115, v4, vcc
	v_cmp_lt_f32_e64 vcc, |v3|, s45
	s_nop 1
	v_cndmask_b32_e32 v3, v4, v3, vcc
